# attention LDS images made bank-conflict-free: K pitch 416B with key rows permuted per 32-key block, V^T pitch 160B read by ds_read_b128 (was ds_read2_b64)
# speedup vs baseline: 1.0134x; 1.0014x over previous
; #define GAS __attribute__((address_space(1)))
; #define DUP(k, stmt) do { stmt; if (((MK_DUP) >> (k)) & 1u) { stmt; } } while (0)
; DI void u_attn2(Frame& F, int h, int qb, int sp, int ntile) {
;     ...
;     const bf16* QM = (const bf16*)(ws + WS_QM); const bf16* KM = (const bf16*)(ws + WS_KM) + h * 192; const bf16* VT = (const bf16*)(ws + WS_VT) + (size_t)(h * 128) * S;
;     const int q0 = qb * 256 + w * 32, cw = 4 * qb + (w >> 1);
;     bf16x8 qf[2][6];
; #pragma unroll
;     for (int qq = 0; qq < 2; ++qq)
; #pragma unroll
;         for (int ks = 0; ks < 6; ++ks) qf[qq][ks] = *(const GAS bf16x8*)(QM + (size_t)(q0 + qq * 16 + lc) * 768 + h * 192 + ks * 32 + g4 * 8);
;     f32x4 o[8][2]; float mrun[2], lrun[2];
; #pragma unroll
;     for (int db = 0; db < 8; ++db)
; #pragma unroll
;         for (int qq = 0; qq < 2; ++qq) o[db][qq] = (f32x4){0.f, 0.f, 0.f, 0.f};
;     mrun[0] = mrun[1] = -1e30f; lrun[0] = lrun[1] = 0.f;
;     u32x4 kreg[3], vreg[2];
;     const int kt0 = 16 * sp;
; __global__ void __launch_bounds__(NTHR, 2) mk_fwd(Args args) {
;     ...
;                 { const int* tab = (const int*)(ws + WS_ATAB);
;                   for (int r = 0; r * NB < ATT_NSUB; ++r) { const int pos = (r & 1) ? NB - 1 - b : b; const int i = r * NB + pos;
;                       if (i < ATT_NSUB) { const int e = tab[i]; DUP(0, u_attn2(F, e & 3, (e >> 2) & 31, (e >> 7) & 31, e >> 12)); } } }
.LBB0_2232:
	s_bitcmp0_b32 s44, 0
	s_cselect_b32 s31, s9, s41
	s_add_i32 s30, s31, s30
	s_cmpk_gt_i32 s30, 0x23f
	s_cbranch_scc1 .LBB0_2231
	s_ashr_i32 s31, s30, 31
	s_lshl_b64 s[30:31], s[30:31], 2
	s_add_u32 s30, s25, s30
	s_addc_u32 s31, s40, s31
	v_mov_b64_e32 v[2:3], s[30:31]
	flat_load_dword v138, v[2:3]
	v_mov_b32_e32 v158, v159
	v_mov_b32_e32 v20, v19
	v_mov_b32_e32 v21, v19
	v_mov_b32_e32 v18, v19
	v_mov_b64_e32 v[64:65], v[20:21]
	v_mov_b64_e32 v[56:57], v[20:21]
	v_mov_b64_e32 v[60:61], v[20:21]
	v_mov_b64_e32 v[68:69], v[20:21]
	v_mov_b64_e32 v[136:137], v[20:21]
	v_mov_b64_e32 v[120:121], v[20:21]
	v_mov_b64_e32 v[108:109], v[20:21]
	v_mov_b64_e32 v[104:105], v[20:21]
	v_mov_b64_e32 v[100:101], v[20:21]
	v_mov_b64_e32 v[96:97], v[20:21]
	v_mov_b64_e32 v[92:93], v[20:21]
	v_mov_b64_e32 v[88:89], v[20:21]
	v_mov_b64_e32 v[84:85], v[20:21]
	v_mov_b64_e32 v[80:81], v[20:21]
	v_mov_b64_e32 v[72:73], v[20:21]
	v_mov_b64_e32 v[76:77], v[20:21]
	v_bfe_u32 v2, v158, 4, 2
	s_mov_b32 s46, 0
	v_mov_b32_e32 v164, 0xf149f2ca
	v_mov_b32_e32 v165, 0
	v_mov_b32_e32 v163, 0
	v_mov_b32_e32 v162, 0xf149f2ca
	v_mov_b64_e32 v[62:63], v[18:19]
	v_mov_b64_e32 v[54:55], v[18:19]
	v_mov_b64_e32 v[58:59], v[18:19]
	v_mov_b64_e32 v[66:67], v[18:19]
	v_mov_b64_e32 v[134:135], v[18:19]
	v_mov_b64_e32 v[118:119], v[18:19]
	v_mov_b64_e32 v[106:107], v[18:19]
	v_mov_b64_e32 v[102:103], v[18:19]
	v_mov_b64_e32 v[98:99], v[18:19]
	v_mov_b64_e32 v[94:95], v[18:19]
	v_mov_b64_e32 v[90:91], v[18:19]
	v_mov_b64_e32 v[86:87], v[18:19]
	v_mov_b64_e32 v[82:83], v[18:19]
	v_mov_b64_e32 v[78:79], v[18:19]
	v_mov_b64_e32 v[70:71], v[18:19]
	v_and_b32_e32 v161, 15, v158
	v_lshlrev_b32_e32 v160, 3, v2
	v_mov_b64_e32 v[74:75], v[18:19]
	s_waitcnt vmcnt(0) lgkmcnt(0)
	v_ashrrev_i32_e32 v179, 12, v138
	v_and_b32_e32 v178, 3, v138
	v_bfe_u32 v177, v138, 2, 5
	v_bfe_u32 v176, v138, 7, 5
	v_cmp_lt_i32_e32 vcc, 0, v179
	s_and_saveexec_b64 s[30:31], vcc
	s_cbranch_execz .LBB0_2245
	v_mul_u32_u24_e32 v3, 0xc0, v178
	v_lshl_add_u32 v4, v177, 8, s42
	v_lshlrev_b32_e32 v18, 1, v3
	v_or_b32_e32 v30, v4, v161
	v_lshl_add_u64 v[4:5], s[12:13], 0, v[18:19]
	v_lshlrev_b32_e32 v2, 4, v2
	v_mov_b32_e32 v3, v19
	v_lshl_add_u64 v[20:21], v[4:5], 0, v[2:3]
	s_movk_i32 s38, 0x600
	v_mad_i64_i32 v[26:27], s[36:37], v30, s38, v[20:21]
	v_or_b32_e32 v30, 16, v30
	v_mad_i64_i32 v[20:21], s[36:37], v30, s38, v[20:21]
	s_mov_b32 s36, 0x2aaaaaab
	global_load_dwordx4 v[2:5], v[26:27], off
	global_load_dwordx4 v[6:9], v[26:27], off offset:64
	global_load_dwordx4 v[10:13], v[26:27], off offset:128
	global_load_dwordx4 v[14:17], v[26:27], off offset:192
	global_load_dwordx4 v[22:25], v[26:27], off offset:256
	s_nop 0
	global_load_dwordx4 v[26:29], v[26:27], off offset:320
	s_nop 0
	global_load_dwordx4 v[30:33], v[20:21], off
	global_load_dwordx4 v[34:37], v[20:21], off offset:64
	global_load_dwordx4 v[38:41], v[20:21], off offset:128
	global_load_dwordx4 v[42:45], v[20:21], off offset:192
	global_load_dwordx4 v[46:49], v[20:21], off offset:256
	global_load_dwordx4 v[50:53], v[20:21], off offset:320
	v_mul_hi_i32 v20, v158, s36
	v_lshrrev_b32_e32 v21, 31, v20
	v_ashrrev_i32_e32 v20, 2, v20
	v_add_u32_e32 v80, v20, v21
	v_add_u32_e32 v20, 0x200, v158
	v_mul_hi_i32 v21, v20, s36
	v_lshrrev_b32_e32 v54, 31, v21
	v_ashrrev_i32_e32 v21, 2, v21
	v_add_u32_e32 v81, v21, v54
	v_add_u32_e32 v54, 0x400, v158
	v_mul_hi_i32 v21, v54, s36
	v_lshrrev_b32_e32 v55, 31, v21
	v_ashrrev_i32_e32 v21, 2, v21
	v_add_u32_e32 v82, v21, v55
	s_movk_i32 s39, 0xffe8
	v_mad_u64_u32 v[54:55], s[36:37], v82, s39, v[54:55]
	v_lshlrev_b32_e32 v74, 21, v178
	v_mov_b32_e32 v75, v19
	v_ashrrev_i32_e32 v56, 3, v158
	v_ashrrev_i32_e32 v60, 3, v20
	v_lshl_add_u64 v[74:75], s[18:19], 0, v[74:75]
	v_lshlrev_b32_e32 v76, 11, v176
	v_mov_b32_e32 v77, v19
	v_lshlrev_b32_e32 v55, 4, v158
	v_ashrrev_i32_e32 v57, 31, v56
	v_ashrrev_i32_e32 v61, 31, v60
	v_mad_u64_u32 v[20:21], s[36:37], v81, s39, v[20:21]
	v_lshl_add_u64 v[74:75], v[74:75], 0, v[76:77]
	v_and_b32_e32 v76, 0x70, v55
	v_lshlrev_b64 v[58:59], 14, v[56:57]
	v_lshlrev_b64 v[62:63], 14, v[60:61]
	v_lshlrev_b32_e32 v64, 3, v54
	v_lshlrev_b32_e32 v21, 10, v176
	v_lshl_add_u64 v[74:75], v[74:75], 0, v[76:77]
	v_ashrrev_i32_e32 v65, 31, v64
	v_lshlrev_b32_e32 v66, 3, v20
	v_mad_u64_u32 v[68:69], s[36:37], v80, s39, v[158:159]
	v_lshl_add_u64 v[72:73], s[16:17], 0, v[18:19]
	v_lshl_add_u64 v[78:79], v[74:75], 0, v[62:63]
	v_lshl_add_u64 v[74:75], v[74:75], 0, v[58:59]
	v_add_u32_e32 v61, v82, v21
	v_ashrrev_i32_e32 v67, 31, v66
	v_mad_i64_i32 v[74:75], s[36:37], v61, s38, v[72:73]
	v_lshlrev_b64 v[64:65], 1, v[64:65]
	v_add_u32_e32 v69, v81, v21
	v_lshlrev_b32_e32 v70, 3, v68
	v_lshl_add_u64 v[74:75], v[74:75], 0, v[64:65]
	v_mad_i64_i32 v[78:79], s[36:37], v69, s38, v[72:73]
	v_lshlrev_b64 v[66:67], 1, v[66:67]
	v_ashrrev_i32_e32 v71, 31, v70
	v_lshl_add_u64 v[78:79], v[78:79], 0, v[66:67]
	v_add_u32_e32 v74, v21, v80
	v_mad_i64_i32 v[72:73], s[36:37], v74, s38, v[72:73]
	v_lshlrev_b64 v[70:71], 1, v[70:71]
	v_lshl_add_u64 v[72:73], v[72:73], 0, v[70:71]
	v_and_b32_e32 v21, 48, v158
	v_add_u32_e32 v73, s11, v21
	v_mov_b32_e32 v21, s11
	s_movk_i32 s36, 0x190
	v_mad_u32_u24 v77, v161, s90, v21
	v_mul_lo_u32 v21, v80, s36
	v_add_u32_e32 v79, s11, v21
	v_mul_lo_u32 v21, v81, s36
	v_lshlrev_b32_e32 v81, 4, v20
	v_mul_lo_u32 v20, v82, s36
	v_add_u32_e32 v82, s11, v20
	v_or_b32_e32 v20, 16, v161
	v_mul_u32_u24_e32 v86, 0x90, v20
	v_mov_b32_e32 v20, 0x3d000000
	v_add_u32_e32 v80, s11, v21
	v_mul_lo_u32 v84, v56, s90
	v_lshl_or_b32 v20, v178, 21, v20
	v_mov_b32_e32 v21, v19
	v_lshlrev_b32_e32 v56, 4, v138
	v_lshlrev_b32_e32 v83, 4, v54
	v_lshl_add_u64 v[54:55], v[20:21], 0, v[62:63]
	v_and_b32_e32 v56, 0xf800, v56
	v_mov_b32_e32 v57, v19
	v_lshl_add_u64 v[20:21], v[20:21], 0, v[58:59]
	v_lshl_add_u64 v[168:169], v[20:21], 0, v[56:57]
	v_mad_i64_i32 v[20:21], s[36:37], v61, s38, v[64:65]
	v_lshl_add_u64 v[20:21], v[20:21], 0, v[18:19]
	s_mov_b64 s[48:49], 0x3c418000
	v_lshl_add_u64 v[170:171], v[20:21], 0, s[48:49]
	v_mad_i64_i32 v[20:21], s[36:37], v69, s38, v[66:67]
	v_lshl_add_u64 v[20:21], v[20:21], 0, v[18:19]
	v_lshl_add_u64 v[172:173], v[20:21], 0, s[48:49]
	v_mad_i64_i32 v[20:21], s[36:37], v74, s38, v[70:71]
	v_lshl_add_u64 v[20:21], v[20:21], 0, v[18:19]
	v_add_u32_e32 v72, s11, v76
	v_mul_u32_u24_e32 v75, 0x90, v161
	v_add_u32_e32 v78, s11, v160
	v_lshlrev_b32_e32 v68, 4, v68
	v_mul_lo_u32 v60, v60, s90
	v_mul_u32_u24_e32 v85, 0x1a0, v161
	v_lshl_add_u64 v[166:167], v[54:55], 0, v[56:57]
	v_lshl_add_u64 v[174:175], v[20:21], 0, s[48:49]
	v_mov_b32_e32 v20, v19
	v_mov_b32_e32 v21, v19
	v_or_b32_e32 v166, v166, v76
	v_or_b32_e32 v168, v168, v76
	v_mov_b32_e32 v18, v19
	v_add_u32_e32 v182, v79, v68
	v_add_u32_e32 v183, v80, v81
	v_add_u32_e32 v184, v82, v83
	v_add_u32_e32 v185, v72, v84
	v_add_u32_e32 v186, v72, v60
	v_add_u32_e32 v187, v73, v85
	v_add_u32_e32 v188, v77, v160
	v_add_u32_e32 v189, v78, v86
	v_add_u32_e32 v190, v78, v75
	v_mov_b64_e32 v[76:77], v[20:21]
	v_mov_b64_e32 v[72:73], v[20:21]
	v_mov_b64_e32 v[80:81], v[20:21]
	v_mov_b64_e32 v[84:85], v[20:21]
	v_mov_b64_e32 v[88:89], v[20:21]
	v_mov_b64_e32 v[92:93], v[20:21]
	v_mov_b64_e32 v[96:97], v[20:21]
	v_mov_b64_e32 v[100:101], v[20:21]
	v_mov_b64_e32 v[104:105], v[20:21]
	v_mov_b64_e32 v[108:109], v[20:21]
	v_mov_b64_e32 v[120:121], v[20:21]
	v_mov_b64_e32 v[136:137], v[20:21]
	v_mov_b64_e32 v[68:69], v[20:21]
	v_mov_b64_e32 v[60:61], v[20:21]
	v_mov_b64_e32 v[56:57], v[20:21]
	v_mov_b64_e32 v[64:65], v[20:21]
	v_lshl_add_u32 v180, v177, 2, s43
	v_lshlrev_b32_e32 v181, 4, v176
	v_mov_b32_e32 v163, 0
	v_mov_b32_e32 v162, 0xf149f2ca
	s_mov_b64 s[36:37], 0
	v_mov_b64_e32 v[74:75], v[18:19]
	v_mov_b64_e32 v[70:71], v[18:19]
	v_mov_b64_e32 v[78:79], v[18:19]
	v_mov_b64_e32 v[82:83], v[18:19]
	v_mov_b64_e32 v[86:87], v[18:19]
	v_mov_b64_e32 v[90:91], v[18:19]
	v_mov_b64_e32 v[94:95], v[18:19]
	v_mov_b64_e32 v[98:99], v[18:19]
	v_mov_b64_e32 v[102:103], v[18:19]
	v_mov_b64_e32 v[106:107], v[18:19]
	v_mov_b64_e32 v[118:119], v[18:19]
	v_mov_b64_e32 v[134:135], v[18:19]
	v_mov_b32_e32 v164, 0xf149f2ca
	v_mov_b32_e32 v165, 0
	v_mov_b64_e32 v[66:67], v[18:19]
	v_mov_b64_e32 v[58:59], v[18:19]
	v_mov_b64_e32 v[54:55], v[18:19]
	v_mov_b64_e32 v[62:63], v[18:19]
	v_readfirstlane_b32 s38, v178
	v_readfirstlane_b32 s39, v176
	v_readfirstlane_b32 s45, v179
	s_mul_i32 s47, s38, 0x180
	s_mul_i32 s37, s39, 0x180000
	s_add_i32 s47, s47, s37
	s_add_u32 s48, s16, s47
	s_addc_u32 s49, s17, 0
	s_lshl_b32 s38, s38, 21
	s_lshl_b32 s39, s39, 11
	s_add_i32 s38, s38, s39
	s_add_u32 s36, s18, s38
	s_addc_u32 s37, s19, 0
	v_and_b32_e32 v114, 63, v158
	v_mul_u32_u24_e32 v116, 0xa0, v161
	v_lshl_add_u32 v116, v160, 1, v116
	v_add_u32_e32 v116, s11, v116
	s_lshl_b32 s47, s24, 6
	v_add_u32_e32 v115, s47, v114
	v_mul_u32_u24_e32 v128, 0x4ed, v115
	v_lshrrev_b32_e32 v128, 15, v128
	v_mul_u32_u24_e32 v129, 26, v128
	v_sub_u32_e32 v129, v115, v129
	v_min_u32_e32 v129, 23, v129
	v_and_b32_e32 v117, 35, v128
	v_and_b32_e32 v130, 12, v128
	v_lshl_or_b32 v117, v130, 1, v117
	v_and_b32_e32 v130, 16, v128
	v_lshrrev_b32_e32 v130, 2, v130
	v_or_b32_e32 v117, v117, v130
	v_mul_u32_u24_e32 v117, 0x600, v117
	v_lshl_add_u32 v122, v129, 4, v117
	v_add_u32_e32 v115, 0x200, v115
	v_mul_u32_u24_e32 v128, 0x4ed, v115
	v_lshrrev_b32_e32 v128, 15, v128
	v_mul_u32_u24_e32 v129, 26, v128
	v_sub_u32_e32 v129, v115, v129
	v_min_u32_e32 v129, 23, v129
	v_and_b32_e32 v117, 35, v128
	v_and_b32_e32 v130, 12, v128
	v_lshl_or_b32 v117, v130, 1, v117
	v_and_b32_e32 v130, 16, v128
	v_lshrrev_b32_e32 v130, 2, v130
	v_or_b32_e32 v117, v117, v130
	v_mul_u32_u24_e32 v117, 0x600, v117
	v_lshl_add_u32 v123, v129, 4, v117
	v_add_u32_e32 v115, 0x200, v115
	v_mul_u32_u24_e32 v128, 0x4ed, v115
	v_lshrrev_b32_e32 v128, 15, v128
	v_mul_u32_u24_e32 v129, 26, v128
	v_sub_u32_e32 v129, v115, v129
	v_min_u32_e32 v129, 23, v129
	v_and_b32_e32 v117, 35, v128
	v_and_b32_e32 v130, 12, v128
	v_lshl_or_b32 v117, v130, 1, v117
	v_and_b32_e32 v130, 16, v128
	v_lshrrev_b32_e32 v130, 2, v130
	v_or_b32_e32 v117, v117, v130
	v_mul_u32_u24_e32 v117, 0x600, v117
	v_lshl_add_u32 v124, v129, 4, v117
	v_add_u32_e32 v115, s47, v114
	v_mul_u32_u24_e32 v128, 0x667, v115
	v_lshrrev_b32_e32 v128, 14, v128
	v_mul_u32_u24_e32 v129, 10, v128
	v_sub_u32_e32 v129, v115, v129
	v_min_u32_e32 v129, 7, v129
	v_lshlrev_b32_e32 v128, 14, v128
	v_lshl_add_u32 v125, v129, 4, v128
	v_add_u32_e32 v115, 0x200, v115
	v_mul_u32_u24_e32 v128, 0x667, v115
	v_lshrrev_b32_e32 v128, 14, v128
	v_mul_u32_u24_e32 v129, 10, v128
	v_sub_u32_e32 v129, v115, v129
	v_min_u32_e32 v129, 7, v129
	v_lshlrev_b32_e32 v128, 14, v128
	v_lshl_add_u32 v126, v129, 4, v128
	s_cmp_lt_u32 s24, 2
	s_cbranch_scc0 .Latt_xv
	s_addk_i32 s47, 0x600
	v_add_u32_e32 v115, s47, v114
	v_mul_u32_u24_e32 v128, 0x4ed, v115
	v_lshrrev_b32_e32 v128, 15, v128
	v_mul_u32_u24_e32 v129, 26, v128
	v_sub_u32_e32 v129, v115, v129
	v_min_u32_e32 v129, 23, v129
	v_and_b32_e32 v117, 35, v128
	v_and_b32_e32 v130, 12, v128
	v_lshl_or_b32 v117, v130, 1, v117
	v_and_b32_e32 v130, 16, v128
	v_lshrrev_b32_e32 v130, 2, v130
	v_or_b32_e32 v117, v117, v130
	v_mul_u32_u24_e32 v117, 0x600, v117
	v_lshl_add_u32 v127, v129, 4, v117
	s_branch .Latt_xdone
; DI void u_attn2(Frame& F, int h, int qb, int sp, int ntile) {
;     ...
;     AT_LOAD(kt0)
.Latt_xv:
	s_min_u32 s47, s24, 5
	s_lshl_b32 s47, s47, 6
	s_addk_i32 s47, 0x380
	v_add_u32_e32 v115, s47, v114
	v_mul_u32_u24_e32 v128, 0x667, v115
	v_lshrrev_b32_e32 v128, 14, v128
	v_mul_u32_u24_e32 v129, 10, v128
	v_sub_u32_e32 v129, v115, v129
	v_min_u32_e32 v129, 7, v129
	v_lshlrev_b32_e32 v128, 14, v128
	v_lshl_add_u32 v127, v129, 4, v128
.Latt_xdone:
	s_lshl_b32 vcc_lo, s24, 10
	s_add_i32 vcc_lo, vcc_lo, s11
	s_mov_b32 m0, vcc_lo
	s_nop 0
	global_load_lds_dwordx4 v122, s[48:49]
	s_add_i32 m0, m0, 0x2000
	s_nop 0
	global_load_lds_dwordx4 v123, s[48:49]
	s_add_i32 m0, m0, 0x2000
	s_nop 0
	global_load_lds_dwordx4 v124, s[48:49]
	s_cmp_lt_u32 s24, 2
	s_cbranch_scc0 .Latt_p1
	s_add_i32 m0, vcc_lo, 0x6000
	s_nop 0
	global_load_lds_dwordx4 v127, s[48:49]
.Latt_p1:
	s_add_u32 s48, s48, 0x18000
	s_addc_u32 s49, s49, 0
	s_add_i32 m0, vcc_lo, 0xb800
	s_nop 0
	global_load_lds_dwordx4 v122, s[48:49]
	s_add_i32 m0, m0, 0x2000
	s_nop 0
	global_load_lds_dwordx4 v123, s[48:49]
	s_add_i32 m0, m0, 0x2000
	s_nop 0
	global_load_lds_dwordx4 v124, s[48:49]
	s_add_i32 m0, vcc_lo, 0x6800
	s_nop 0
	global_load_lds_dwordx4 v125, s[36:37]
	s_add_i32 m0, m0, 0x2000
	s_nop 0
	global_load_lds_dwordx4 v126, s[36:37]
	s_min_u32 vcc_hi, s24, 5
	s_lshl_b32 vcc_hi, vcc_hi, 10
	s_add_i32 vcc_hi, vcc_hi, 0xa000
	s_add_i32 vcc_hi, vcc_hi, s11
	s_add_i32 vcc_lo, vcc_lo, 0x11800
	s_cmp_lt_u32 s24, 2
	s_cselect_b32 m0, vcc_lo, vcc_hi
	s_cselect_b32 s38, s48, s36
	s_cselect_b32 s39, s49, s37
	global_load_lds_dwordx4 v127, s[38:39]
	s_add_u32 s48, s48, 0x18000
	s_addc_u32 s49, s49, 0
	s_add_u32 s36, s36, 0x80
	s_addc_u32 s37, s37, 0
	s_waitcnt vmcnt(6)
	s_mov_b32 s46, 0
	s_mov_b32 s47, 0
	s_branch .LBB0_2237

; #define LAS __attribute__((address_space(3)))
; DI void u_attn2(Frame& F, int h, int qb, int sp, int ntile) {
;     ...
;     for (int t = 0; t < ntile; ++t) {
;         const int kt = kt0 + t;
;         __syncthreads();
; #pragma unroll
;         for (int i = 0; i < 3; ++i) { const int p = tid + 512 * i, r = p / 24, cc = p - r * 24; *(LAS u32x4*)(Ks + r * 200 + cc * 8) = kreg[i]; }
; #pragma unroll
;         for (int i = 0; i < 2; ++i) { const int p = tid + 512 * i, r = p >> 3, cc = p & 7; *(LAS u32x4*)(Vs + r * 72 + cc * 8) = vreg[i]; }
;         __syncthreads();
;         if (t + 1 < ntile) AT_LOAD(kt + 1)
.Latt_w1:
	s_cmp_eq_u32 s46, s45
	s_cbranch_scc1 .LBB0_2244
	s_add_i32 s46, s46, 1
	s_add_i32 s47, s47, 0xb800
	s_cmp_eq_u32 s47, 0x22800
	s_cselect_b32 s47, 0, s47
.LBB0_2237:
	s_barrier
	s_add_i32 s39, s47, 0xb800
	s_cmp_eq_u32 s39, 0x22800
	s_cselect_b32 s39, 0, s39
	s_add_i32 s38, s39, 0xb800
	s_cmp_eq_u32 s38, 0x22800
	s_cselect_b32 s38, 0, s38
	v_add_u32_e32 v113, s47, v187
	v_add_u32_e32 v110, s38, v116
	v_mov_b32_e32 v234, 0x42800000
	s_lshl_b32 vcc_lo, s24, 10
	s_add_i32 vcc_lo, vcc_lo, s11
	s_add_i32 vcc_hi, s46, 2
	s_cmp_lt_i32 vcc_hi, s45
	s_cbranch_scc0 .Latt_vonly
	s_add_i32 m0, s38, vcc_lo
	s_nop 0
	global_load_lds_dwordx4 v122, s[48:49]
	s_add_i32 m0, m0, 0x2000
	s_nop 0
	global_load_lds_dwordx4 v123, s[48:49]
	s_add_i32 m0, m0, 0x2000
	s_nop 0
	global_load_lds_dwordx4 v124, s[48:49]
	s_branch .Latt_vjobs

; #define MFMA16(a, b, c) __builtin_amdgcn_mfma_f32_16x16x32_bf16((a), (b), (c), 0, 0, 0)
; #define AT_VLD(dst, db_) { _Pragma("unroll") for (int s2 = 0; s2 < 2; ++s2) { const LAS bf16* vp = Vs + ((db_) * 16 + lc) * 72 + 32 * s2 + 4 * g4; \
;                     const u32x2 v0 = *(const LAS u32x2*)vp, v1 = *(const LAS u32x2*)(vp + 16); const u32x4 vw = (u32x4){v0.x, v0.y, v1.x, v1.y}; dst[s2] = __builtin_bit_cast(bf16x8, vw); } }
; DI void u_attn2(Frame& F, int h, int qb, int sp, int ntile) {
;     ...
;         if (t + 1 < ntile) AT_LOAD(kt + 1)
;     ...
;             {
;                 bf16x8 vfr[2][2];
;     ...
;                 AT_VLD(vfr[0], 0)
; #pragma unroll
;                 for (int db = 0; db < 8; ++db) {
;                     if (db < 7) AT_VLD(vfr[(db + 1) & 1], db + 1)
; #pragma unroll
;                     for (int s2 = 0; s2 < 2; ++s2)
; #pragma unroll
;                         for (int qq = 0; qq < 2; ++qq) o[db][qq] = MFMA16(vfr[db & 1][s2], pf[qq][s2], o[db][qq]);
;                 }
.Latt_vjobs:
	s_add_i32 vcc_hi, s39, vcc_lo
	s_add_i32 m0, vcc_hi, 0x6800
	s_nop 0
	global_load_lds_dwordx4 v125, s[36:37]
	s_add_i32 m0, m0, 0x2000
	s_nop 0
	global_load_lds_dwordx4 v126, s[36:37]
	s_min_u32 vcc_hi, s24, 5
	s_lshl_b32 vcc_hi, vcc_hi, 10
	s_add_i32 vcc_hi, vcc_hi, s39
	s_add_i32 vcc_hi, vcc_hi, 0xa000
	s_add_i32 vcc_hi, vcc_hi, s11
	s_add_i32 vcc_lo, vcc_lo, s38
	s_add_i32 vcc_lo, vcc_lo, 0x6000
	s_cmp_lt_u32 s24, 2
	s_cselect_b32 m0, vcc_lo, vcc_hi
	s_cselect_b32 s38, s48, s36
	s_cselect_b32 s39, s49, s37
	global_load_lds_dwordx4 v127, s[38:39]
	s_add_u32 s48, s48, 0x18000
	s_addc_u32 s49, s49, 0
	s_add_u32 s36, s36, 0x80
	s_addc_u32 s37, s37, 0
.Latt_noload:
	s_cmp_lt_i32 s24, 4
	s_cbranch_scc0 .Latt_gB
	s_cmp_eq_u32 s46, 0
	s_cbranch_scc1 .Latt_A_qk
	v_add3_u32 v18, s46, v181, -1
	v_cmp_le_i32_e32 vcc, v18, v180
	s_cbranch_vccz .Latt_A_qk
	ds_read_b128 v[146:149], v110 offset:26624
	ds_read_b128 v[244:247], v110 offset:26688
	ds_read_b128 v[220:223], v110 offset:29184
	ds_read_b128 v[224:227], v110 offset:29248
	s_waitcnt lgkmcnt(3)
	v_mfma_f32_16x16x32_bf16 v[134:137], v[146:149], v[198:201], v[134:137]
	v_mfma_f32_16x16x32_bf16 v[118:121], v[146:149], v[210:213], v[118:121]
	ds_read_b128 v[146:149], v110 offset:31744
	s_waitcnt lgkmcnt(3)
	v_mfma_f32_16x16x32_bf16 v[134:137], v[244:247], v[192:195], v[134:137]
	v_mfma_f32_16x16x32_bf16 v[118:121], v[244:247], v[142:145], v[118:121]
	ds_read_b128 v[244:247], v110 offset:31808
	s_waitcnt lgkmcnt(3)
	v_mfma_f32_16x16x32_bf16 v[106:109], v[220:223], v[198:201], v[106:109]
	v_mfma_f32_16x16x32_bf16 v[102:105], v[220:223], v[210:213], v[102:105]
	ds_read_b128 v[220:223], v110 offset:34304
	s_waitcnt lgkmcnt(3)
	v_mfma_f32_16x16x32_bf16 v[106:109], v[224:227], v[192:195], v[106:109]
	v_mfma_f32_16x16x32_bf16 v[102:105], v[224:227], v[142:145], v[102:105]
	ds_read_b128 v[224:227], v110 offset:34368
	s_waitcnt lgkmcnt(3)
	v_mfma_f32_16x16x32_bf16 v[98:101], v[146:149], v[198:201], v[98:101]
	v_mfma_f32_16x16x32_bf16 v[94:97], v[146:149], v[210:213], v[94:97]
	ds_read_b128 v[146:149], v110 offset:36864
	s_waitcnt lgkmcnt(3)
	v_mfma_f32_16x16x32_bf16 v[98:101], v[244:247], v[192:195], v[98:101]
	v_mfma_f32_16x16x32_bf16 v[94:97], v[244:247], v[142:145], v[94:97]
	ds_read_b128 v[244:247], v110 offset:36928
	s_waitcnt lgkmcnt(3)
	v_mfma_f32_16x16x32_bf16 v[90:93], v[220:223], v[198:201], v[90:93]
	v_mfma_f32_16x16x32_bf16 v[86:89], v[220:223], v[210:213], v[86:89]
	ds_read_b128 v[220:223], v110 offset:39424
	s_waitcnt lgkmcnt(3)
	v_mfma_f32_16x16x32_bf16 v[90:93], v[224:227], v[192:195], v[90:93]
	v_mfma_f32_16x16x32_bf16 v[86:89], v[224:227], v[142:145], v[86:89]
	ds_read_b128 v[224:227], v110 offset:39488
	s_waitcnt lgkmcnt(3)
	v_mfma_f32_16x16x32_bf16 v[82:85], v[146:149], v[198:201], v[82:85]
	v_mfma_f32_16x16x32_bf16 v[78:81], v[146:149], v[210:213], v[78:81]
	ds_read_b128 v[146:149], v110 offset:41984
	s_waitcnt lgkmcnt(3)
	v_mfma_f32_16x16x32_bf16 v[82:85], v[244:247], v[192:195], v[82:85]
	v_mfma_f32_16x16x32_bf16 v[78:81], v[244:247], v[142:145], v[78:81]
	ds_read_b128 v[244:247], v110 offset:42048
	s_waitcnt lgkmcnt(3)
	v_mfma_f32_16x16x32_bf16 v[70:73], v[220:223], v[198:201], v[70:73]
	v_mfma_f32_16x16x32_bf16 v[74:77], v[220:223], v[210:213], v[74:77]
	ds_read_b128 v[220:223], v110 offset:44544
	s_waitcnt lgkmcnt(3)
	v_mfma_f32_16x16x32_bf16 v[70:73], v[224:227], v[192:195], v[70:73]
	v_mfma_f32_16x16x32_bf16 v[74:77], v[224:227], v[142:145], v[74:77]
	ds_read_b128 v[224:227], v110 offset:44608
	s_waitcnt lgkmcnt(3)
	v_mfma_f32_16x16x32_bf16 v[66:69], v[146:149], v[198:201], v[66:69]
	v_mfma_f32_16x16x32_bf16 v[58:61], v[146:149], v[210:213], v[58:61]
	s_waitcnt lgkmcnt(2)
	v_mfma_f32_16x16x32_bf16 v[66:69], v[244:247], v[192:195], v[66:69]
	v_mfma_f32_16x16x32_bf16 v[58:61], v[244:247], v[142:145], v[58:61]
	s_waitcnt lgkmcnt(1)
	v_mfma_f32_16x16x32_bf16 v[54:57], v[220:223], v[198:201], v[54:57]
	v_mfma_f32_16x16x32_bf16 v[62:65], v[220:223], v[210:213], v[62:65]
	s_waitcnt lgkmcnt(0)
	v_mfma_f32_16x16x32_bf16 v[54:57], v[224:227], v[192:195], v[54:57]
	v_mfma_f32_16x16x32_bf16 v[62:65], v[224:227], v[142:145], v[62:65]
.Latt_A_qk:
	v_cmp_lt_i32_e32 vcc, s46, v179
	s_cbranch_vccz .LBB0_2236
	v_add_u32_e32 v18, s46, v181
	v_cmp_le_i32_e32 vcc, v18, v180
	s_cbranch_vccz .LBB0_2236
; DI float xr16_max(float x) { float a = x, b = x; XR_SWAP("v_permlane16_swap_b32", a, b); return fmaxf(a, b); }
; DI float xr32_max(float x) { float a = x, b = x; XR_SWAP("v_permlane32_swap_b32", a, b); return fmaxf(a, b); }
; DI float xr16_sum(float x) { float a = x, b = x; XR_SWAP("v_permlane16_swap_b32", a, b); return a + b; }
; DI float xr32_sum(float x) { float a = x, b = x; XR_SWAP("v_permlane32_swap_b32", a, b); return a + b; }
; #define MFMA16(a, b, c) __builtin_amdgcn_mfma_f32_16x16x32_bf16((a), (b), (c), 0, 0, 0)
; DI void u_attn2(Frame& F, int h, int qb, int sp, int ntile) {
;     ...
;             {
;                 bf16x8 kfr[2][4];
; #pragma unroll
;                 for (int kb = 0; kb < 4; ++kb) kfr[0][kb] = ldfrag(Ks, 200, kb * 16, 0, lane);
; #pragma unroll
;                 for (int ks = 0; ks < 6; ++ks) {
;                     if (ks < 5) {
; #pragma unroll
;                         for (int kb = 0; kb < 4; ++kb) kfr[(ks + 1) & 1][kb] = ldfrag(Ks, 200, kb * 16, (ks + 1) * 32, lane); }
; #pragma unroll
;                     for (int kb = 0; kb < 4; ++kb)
; #pragma unroll
;                         for (int qq = 0; qq < 2; ++qq) s[kb][qq] = MFMA16(kfr[ks & 1][kb], qf[qq][ks], s[kb][qq]);
;                 }
;             }
;             bf16x8 pf[2][2];
; #pragma unroll
;             for (int qq = 0; qq < 2; ++qq) {
;                 float mx = -1e30f;
; #pragma unroll
;                 for (int kb = 0; kb < 4; ++kb) mx = fmaxf(mx, fmaxf(fmaxf(s[kb][qq][0], s[kb][qq][1]), fmaxf(s[kb][qq][2], s[kb][qq][3])));
;                 mx = xr32_max(xr16_max(mx));
;                 const float mn = fmaxf(mrun[qq], mx), alpha = __builtin_amdgcn_exp2f(mrun[qq] - mn); mrun[qq] = mn;
;                 float ps = 0.f; float p[16];
; #pragma unroll
;                 for (int kb = 0; kb < 4; ++kb)
; #pragma unroll
;                     for (int r = 0; r < 4; ++r) { p[kb * 4 + r] = __builtin_amdgcn_exp2f(s[kb][qq][r] - mn); ps += p[kb * 4 + r]; }
;                 ps = xr32_sum(xr16_sum(ps));
;                 lrun[qq] = lrun[qq] * alpha + ps;
; if (__builtin_amdgcn_ballot_w64(alpha != 1.0f) != 0ull) {
; #pragma unroll
;                     for (int db = 0; db < 8; ++db) o[db][qq] = o[db][qq] * alpha; }
	ds_read_b128 v[138:141], v113
	ds_read_b128 v[142:145], v113 offset:6656
	ds_read_b128 v[146:149], v113 offset:13312
	ds_read_b128 v[150:153], v113 offset:19968
	ds_read_b128 v[154:157], v113 offset:64
	ds_read_b128 v[192:195], v113 offset:6720
	ds_read_b128 v[210:213], v113 offset:13376
	ds_read_b128 v[214:217], v113 offset:20032
	s_waitcnt lgkmcnt(7)
	v_mfma_f32_16x16x32_bf16 v[218:221], v[138:141], v[2:5], 0
	ds_read_b128 v[244:247], v113 offset:128
	ds_read_b128 v[248:251], v113 offset:6784
	ds_read_b128 v[198:201], v113 offset:13440
	ds_read_b128 v[230:233], v113 offset:20096
	v_mov_b32_e32 v234, 0x42800000
	v_mfma_f32_16x16x32_bf16 v[138:141], v[138:141], v[30:33], 0
	s_waitcnt lgkmcnt(10)
	v_mfma_f32_16x16x32_bf16 v[222:225], v[142:145], v[2:5], 0
	v_mfma_f32_16x16x32_bf16 v[142:145], v[142:145], v[30:33], 0
	s_waitcnt lgkmcnt(9)
	v_mfma_f32_16x16x32_bf16 v[226:229], v[146:149], v[2:5], 0
	s_waitcnt lgkmcnt(7)
	v_mfma_f32_16x16x32_bf16 v[218:221], v[154:157], v[6:9], v[218:221]
	v_mfma_f32_16x16x32_bf16 v[146:149], v[146:149], v[30:33], 0
	v_mfma_f32_16x16x32_bf16 v[240:243], v[150:153], v[2:5], 0
	v_mfma_f32_16x16x32_bf16 v[150:153], v[150:153], v[30:33], 0
	v_mfma_f32_16x16x32_bf16 v[138:141], v[154:157], v[34:37], v[138:141]
	s_waitcnt lgkmcnt(6)
	v_mfma_f32_16x16x32_bf16 v[154:157], v[192:195], v[6:9], v[222:225]
	v_mfma_f32_16x16x32_bf16 v[142:145], v[192:195], v[34:37], v[142:145]
	s_waitcnt lgkmcnt(5)
	v_mfma_f32_16x16x32_bf16 v[192:195], v[210:213], v[6:9], v[226:229]
	s_waitcnt lgkmcnt(3)
	v_mfma_f32_16x16x32_bf16 v[218:221], v[244:247], v[10:13], v[218:221]
	v_mfma_f32_16x16x32_bf16 v[146:149], v[210:213], v[34:37], v[146:149]
	v_mfma_f32_16x16x32_bf16 v[210:213], v[214:217], v[6:9], v[240:243]
	v_mfma_f32_16x16x32_bf16 v[150:153], v[214:217], v[34:37], v[150:153]
	ds_read_b128 v[214:217], v113 offset:192
	ds_read_b128 v[222:225], v113 offset:6848
	ds_read_b128 v[226:229], v113 offset:13504
	ds_read_b128 v[240:243], v113 offset:20160
	v_mfma_f32_16x16x32_bf16 v[138:141], v[244:247], v[38:41], v[138:141]
	s_waitcnt lgkmcnt(6)
	v_mfma_f32_16x16x32_bf16 v[154:157], v[248:251], v[10:13], v[154:157]
	v_mfma_f32_16x16x32_bf16 v[142:145], v[248:251], v[38:41], v[142:145]
	s_waitcnt lgkmcnt(5)
	v_mfma_f32_16x16x32_bf16 v[192:195], v[198:201], v[10:13], v[192:195]
	s_waitcnt lgkmcnt(3)
	v_mfma_f32_16x16x32_bf16 v[218:221], v[214:217], v[14:17], v[218:221]
	v_mfma_f32_16x16x32_bf16 v[146:149], v[198:201], v[38:41], v[146:149]
	v_mfma_f32_16x16x32_bf16 v[198:201], v[230:233], v[10:13], v[210:213]
	v_mfma_f32_16x16x32_bf16 v[150:153], v[230:233], v[38:41], v[150:153]
	s_nop 1
	ds_read_b128 v[210:213], v113 offset:256
	ds_read_b128 v[230:233], v113 offset:6912
	ds_read_b128 v[244:247], v113 offset:13568
	ds_read_b128 v[248:251], v113 offset:20224
	v_mfma_f32_16x16x32_bf16 v[138:141], v[214:217], v[42:45], v[138:141]
	s_waitcnt lgkmcnt(6)
	v_mfma_f32_16x16x32_bf16 v[154:157], v[222:225], v[14:17], v[154:157]
	v_mfma_f32_16x16x32_bf16 v[142:145], v[222:225], v[42:45], v[142:145]
	s_waitcnt lgkmcnt(5)
	v_mfma_f32_16x16x32_bf16 v[192:195], v[226:229], v[14:17], v[192:195]
	s_waitcnt lgkmcnt(3)
	v_mfma_f32_16x16x32_bf16 v[218:221], v[210:213], v[22:25], v[218:221]
	v_mfma_f32_16x16x32_bf16 v[198:201], v[240:243], v[14:17], v[198:201]
	v_mfma_f32_16x16x32_bf16 v[150:153], v[240:243], v[42:45], v[150:153]
	v_mfma_f32_16x16x32_bf16 v[138:141], v[210:213], v[46:49], v[138:141]
	s_waitcnt lgkmcnt(2)
	v_mfma_f32_16x16x32_bf16 v[154:157], v[230:233], v[22:25], v[154:157]
	v_mfma_f32_16x16x32_bf16 v[146:149], v[226:229], v[42:45], v[146:149]
	ds_read_b128 v[214:217], v113 offset:320
	ds_read_b128 v[222:225], v113 offset:6976
	ds_read_b128 v[226:229], v113 offset:13632
	ds_read_b128 v[240:243], v113 offset:20288
	v_mfma_f32_16x16x32_bf16 v[142:145], v[230:233], v[46:49], v[142:145]
	s_waitcnt lgkmcnt(5)
	v_mfma_f32_16x16x32_bf16 v[192:195], v[244:247], v[22:25], v[192:195]
	s_waitcnt lgkmcnt(3)
	v_mfma_f32_16x16x32_bf16 v[218:221], v[214:217], v[26:29], v[218:221]
	v_mfma_f32_16x16x32_bf16 v[198:201], v[248:251], v[22:25], v[198:201]
	v_mfma_f32_16x16x32_bf16 v[230:233], v[248:251], v[46:49], v[150:153]
	v_mfma_f32_16x16x32_bf16 v[150:153], v[214:217], v[50:53], v[138:141]
	s_waitcnt lgkmcnt(2)
	v_mfma_f32_16x16x32_bf16 v[214:217], v[222:225], v[26:29], v[154:157]
	v_mfma_f32_16x16x32_bf16 v[210:213], v[244:247], v[46:49], v[146:149]
	v_mfma_f32_16x16x32_bf16 v[146:149], v[222:225], v[50:53], v[142:145]
	s_waitcnt lgkmcnt(1)
	v_mfma_f32_16x16x32_bf16 v[222:225], v[226:229], v[26:29], v[192:195]
	s_waitcnt lgkmcnt(0)
	v_mfma_f32_16x16x32_bf16 v[154:157], v[240:243], v[26:29], v[198:201]
	v_mfma_f32_16x16x32_bf16 v[138:141], v[240:243], v[50:53], v[230:233]
	s_nop 1
	v_mfma_f32_16x16x32_bf16 v[142:145], v[226:229], v[50:53], v[210:213]
	s_nop 7
	s_nop 1
	v_max3_f32 v198, v218, v219, v220
	v_max3_f32 v210, v150, v151, v152
	v_max3_f32 v199, v221, v214, v215
	v_max3_f32 v211, v153, v146, v147
	v_max3_f32 v200, v216, v217, v222
	v_max3_f32 v212, v148, v149, v142
	v_max3_f32 v201, v223, v224, v225
	v_max3_f32 v213, v143, v144, v145
	v_max3_f32 v192, v154, v155, v156
	v_max3_f32 v193, v138, v139, v140
	v_max3_f32 v198, v198, v199, v157
	v_max3_f32 v210, v210, v211, v141
	v_max3_f32 v200, v200, v201, v192
	v_max3_f32 v212, v212, v213, v193
	v_max3_f32 v18, v198, v200, s1
	v_max3_f32 v20, v210, v212, s1
	v_mov_b32_e32 v198, v18
	v_mov_b32_e32 v210, v20
	s_nop 0
	v_permlane16_swap_b32 v18, v198
	v_permlane16_swap_b32 v20, v210
	s_nop 0
	v_max_f32_e32 v18, v18, v198
	v_max_f32_e32 v20, v20, v210
	v_mov_b32_e32 v198, v18
	v_mov_b32_e32 v210, v20
	s_nop 0
	v_permlane32_swap_b32 v18, v198
	v_permlane32_swap_b32 v20, v210
	s_nop 0
	v_max3_f32 v21, v164, v18, v198
	v_max3_f32 v191, v162, v20, v210
	v_sub_f32_e32 v18, v164, v21
	v_sub_f32_e32 v20, v162, v191
	v_exp_f32_e32 v18, v18
	v_exp_f32_e32 v20, v20
	v_sub_f32_e32 v218, v218, v21
	v_sub_f32_e32 v219, v219, v21
	v_sub_f32_e32 v220, v220, v21
	v_sub_f32_e32 v221, v221, v21
	v_sub_f32_e32 v214, v214, v21
	v_sub_f32_e32 v215, v215, v21
	v_sub_f32_e32 v216, v216, v21
	v_sub_f32_e32 v217, v217, v21
	v_sub_f32_e32 v222, v222, v21
	v_sub_f32_e32 v223, v223, v21
	v_sub_f32_e32 v224, v224, v21
	v_sub_f32_e32 v225, v225, v21
	v_sub_f32_e32 v154, v154, v21
	v_sub_f32_e32 v155, v155, v21
	v_sub_f32_e32 v156, v156, v21
	v_sub_f32_e32 v157, v157, v21
	v_sub_f32_e32 v150, v150, v191
	v_sub_f32_e32 v151, v151, v191
	v_sub_f32_e32 v152, v152, v191
	v_sub_f32_e32 v153, v153, v191
	v_sub_f32_e32 v146, v146, v191
	v_sub_f32_e32 v147, v147, v191
	v_sub_f32_e32 v148, v148, v191
	v_sub_f32_e32 v149, v149, v191
	v_sub_f32_e32 v142, v142, v191
	v_sub_f32_e32 v143, v143, v191
	v_sub_f32_e32 v144, v144, v191
	v_sub_f32_e32 v145, v145, v191
	v_sub_f32_e32 v138, v138, v191
	v_sub_f32_e32 v139, v139, v191
	v_sub_f32_e32 v140, v140, v191
	v_sub_f32_e32 v141, v141, v191
	v_cmp_neq_f32_e32 vcc, 1.0, v18
	s_cbranch_vccz .Latt_r0_A
; DI void u_attn2(Frame& F, int h, int qb, int sp, int ntile) {
;     ...
; if (__builtin_amdgcn_ballot_w64(alpha != 1.0f) != 0ull) {
; #pragma unroll
;                     for (int db = 0; db < 8; ++db) o[db][qq] = o[db][qq] * alpha; }
	v_pk_mul_f32 v[136:137], v[136:137], v[18:19] op_sel_hi:[1,0]
	v_pk_mul_f32 v[134:135], v[134:135], v[18:19] op_sel_hi:[1,0]
	v_pk_mul_f32 v[108:109], v[108:109], v[18:19] op_sel_hi:[1,0]
	v_pk_mul_f32 v[106:107], v[106:107], v[18:19] op_sel_hi:[1,0]
	v_pk_mul_f32 v[100:101], v[100:101], v[18:19] op_sel_hi:[1,0]
	v_pk_mul_f32 v[98:99], v[98:99], v[18:19] op_sel_hi:[1,0]
	v_pk_mul_f32 v[92:93], v[92:93], v[18:19] op_sel_hi:[1,0]
	v_pk_mul_f32 v[90:91], v[90:91], v[18:19] op_sel_hi:[1,0]
	v_pk_mul_f32 v[84:85], v[84:85], v[18:19] op_sel_hi:[1,0]
	v_pk_mul_f32 v[82:83], v[82:83], v[18:19] op_sel_hi:[1,0]
	v_pk_mul_f32 v[72:73], v[72:73], v[18:19] op_sel_hi:[1,0]
	v_pk_mul_f32 v[70:71], v[70:71], v[18:19] op_sel_hi:[1,0]
	v_pk_mul_f32 v[68:69], v[68:69], v[18:19] op_sel_hi:[1,0]
	v_pk_mul_f32 v[66:67], v[66:67], v[18:19] op_sel_hi:[1,0]
	v_pk_mul_f32 v[56:57], v[56:57], v[18:19] op_sel_hi:[1,0]
	v_pk_mul_f32 v[54:55], v[54:55], v[18:19] op_sel_hi:[1,0]

; DI unsigned pk2(float lo, float hi) { const f32x2 v = {lo, hi}; const bf16x2_t b = __builtin_convertvector(v, bf16x2_t); return __builtin_bit_cast(unsigned, b); }
; DI float xr16_sum(float x) { float a = x, b = x; XR_SWAP("v_permlane16_swap_b32", a, b); return a + b; }
; DI float xr32_sum(float x) { float a = x, b = x; XR_SWAP("v_permlane32_swap_b32", a, b); return a + b; }
; #define MFMA16(a, b, c) __builtin_amdgcn_mfma_f32_16x16x32_bf16((a), (b), (c), 0, 0, 0)
; #define AT_VLD(dst, db_) { _Pragma("unroll") for (int s2 = 0; s2 < 2; ++s2) { const LAS bf16* vp = Vs + ((db_) * 16 + lc) * 72 + 32 * s2 + 4 * g4; \
;                     const u32x2 v0 = *(const LAS u32x2*)vp, v1 = *(const LAS u32x2*)(vp + 16); const u32x4 vw = (u32x4){v0.x, v0.y, v1.x, v1.y}; dst[s2] = __builtin_bit_cast(bf16x8, vw); } }
; DI void u_attn2(Frame& F, int h, int qb, int sp, int ntile) {
;     ...
;                 const float mn = fmaxf(mrun[qq], mx), alpha = __builtin_amdgcn_exp2f(mrun[qq] - mn); mrun[qq] = mn;
;                 float ps = 0.f; float p[16];
; #pragma unroll
;                 for (int kb = 0; kb < 4; ++kb)
; #pragma unroll
;                     for (int r = 0; r < 4; ++r) { p[kb * 4 + r] = __builtin_amdgcn_exp2f(s[kb][qq][r] - mn); ps += p[kb * 4 + r]; }
;                 ps = xr32_sum(xr16_sum(ps));
;                 lrun[qq] = lrun[qq] * alpha + ps;
; if (__builtin_amdgcn_ballot_w64(alpha != 1.0f) != 0ull) {
; #pragma unroll
;                     for (int db = 0; db < 8; ++db) o[db][qq] = o[db][qq] * alpha; }
; #pragma unroll
;                 for (int s2 = 0; s2 < 2; ++s2) { u32x4 pw; pw.x = pk2(p[8 * s2], p[8 * s2 + 1]); pw.y = pk2(p[8 * s2 + 2], p[8 * s2 + 3]); pw.z = pk2(p[8 * s2 + 4], p[8 * s2 + 5]); pw.w = pk2(p[8 * s2 + 6], p[8 * s2 + 7]); pf[qq][s2] = __builtin_bit_cast(bf16x8, pw); }
;             }
;             {
;                 bf16x8 vfr[2][2];
;     ...
;                 AT_VLD(vfr[0], 0)
; #pragma unroll
;                 for (int db = 0; db < 8; ++db) {
;                     if (db < 7) AT_VLD(vfr[(db + 1) & 1], db + 1)
; #pragma unroll
;                     for (int s2 = 0; s2 < 2; ++s2)
; #pragma unroll
;                         for (int qq = 0; qq < 2; ++qq) o[db][qq] = MFMA16(vfr[db & 1][s2], pf[qq][s2], o[db][qq]);
;                 }
.Latt_r1_B:
	v_exp_f32_e32 v218, v218
	v_exp_f32_e32 v219, v219
	v_exp_f32_e32 v220, v220
	v_exp_f32_e32 v221, v221
	v_exp_f32_e32 v214, v214
	v_exp_f32_e32 v215, v215
	v_exp_f32_e32 v216, v216
	v_exp_f32_e32 v217, v217
	v_exp_f32_e32 v222, v222
	v_exp_f32_e32 v223, v223
	v_exp_f32_e32 v224, v224
	v_exp_f32_e32 v225, v225
	v_exp_f32_e32 v154, v154
	v_exp_f32_e32 v155, v155
	v_exp_f32_e32 v156, v156
	v_exp_f32_e32 v157, v157
	v_exp_f32_e32 v150, v150
	v_exp_f32_e32 v151, v151
	v_exp_f32_e32 v152, v152
	v_exp_f32_e32 v153, v153
	v_exp_f32_e32 v146, v146
	v_exp_f32_e32 v147, v147
	v_exp_f32_e32 v148, v148
	v_exp_f32_e32 v149, v149
	v_exp_f32_e32 v142, v142
	v_exp_f32_e32 v143, v143
	v_exp_f32_e32 v144, v144
	v_exp_f32_e32 v145, v145
	v_exp_f32_e32 v138, v138
	v_exp_f32_e32 v139, v139
	v_exp_f32_e32 v140, v140
	v_exp_f32_e32 v141, v141
	v_add_f32_e32 v198, v218, v219
	v_add_f32_e32 v199, v220, v221
	v_add_f32_e32 v200, v214, v215
	v_add_f32_e32 v201, v216, v217
	v_add_f32_e32 v210, v150, v151
	v_add_f32_e32 v211, v152, v153
	v_add_f32_e32 v212, v146, v147
	v_add_f32_e32 v213, v148, v149
	v_add_f32_e32 v198, v198, v222
	v_add_f32_e32 v199, v199, v223
	v_add_f32_e32 v200, v200, v224
	v_add_f32_e32 v201, v201, v225
	v_add_f32_e32 v210, v210, v142
	v_add_f32_e32 v211, v211, v143
	v_add_f32_e32 v212, v212, v144
	v_add_f32_e32 v213, v213, v145
	v_add_f32_e32 v198, v198, v154
	v_add_f32_e32 v199, v199, v155
	v_add_f32_e32 v200, v200, v156
	v_add_f32_e32 v201, v201, v157
	v_add_f32_e32 v210, v210, v138
	v_add_f32_e32 v211, v211, v139
	v_add_f32_e32 v212, v212, v140
	v_add_f32_e32 v213, v213, v141
	v_add_f32_e32 v198, v198, v199
	v_add_f32_e32 v200, v200, v201
	v_add_f32_e32 v210, v210, v211
	v_add_f32_e32 v212, v212, v213
	v_add_f32_e32 v198, v198, v200
	v_add_f32_e32 v210, v210, v212
	v_mov_b32_e32 v199, v198
	v_mov_b32_e32 v211, v210
	s_nop 0
	v_permlane16_swap_b32 v198, v199
	v_permlane16_swap_b32 v210, v211
	s_nop 0
	v_add_f32_e32 v198, v198, v199
	v_add_f32_e32 v210, v210, v211
	v_mov_b32_e32 v199, v198
	v_mov_b32_e32 v211, v210
	s_nop 0
	v_permlane32_swap_b32 v198, v199
	v_permlane32_swap_b32 v210, v211
	s_nop 0
	v_add_f32_e32 v198, v198, v199
	v_add_f32_e32 v210, v210, v211
	v_fmac_f32_e32 v198, v165, v18
	v_fmac_f32_e32 v210, v163, v20
	v_mov_b32_e32 v164, v21
	v_mov_b32_e32 v162, v191
	v_mov_b32_e32 v165, v198
	v_mov_b32_e32 v163, v210
	v_cvt_pk_bf16_f32 v198, v218, v219
	v_cvt_pk_bf16_f32 v199, v220, v221
	v_cvt_pk_bf16_f32 v200, v214, v215
	v_cvt_pk_bf16_f32 v201, v216, v217
	v_cvt_pk_bf16_f32 v192, v222, v223
	v_cvt_pk_bf16_f32 v193, v224, v225
	v_cvt_pk_bf16_f32 v194, v154, v155
	v_cvt_pk_bf16_f32 v195, v156, v157
	v_cvt_pk_bf16_f32 v210, v150, v151
	v_cvt_pk_bf16_f32 v211, v152, v153
	v_cvt_pk_bf16_f32 v212, v146, v147
	v_cvt_pk_bf16_f32 v213, v148, v149
	v_cvt_pk_bf16_f32 v142, v142, v143
	v_cvt_pk_bf16_f32 v143, v144, v145
	v_cvt_pk_bf16_f32 v144, v138, v139
	v_cvt_pk_bf16_f32 v145, v140, v141
	ds_read_b128 v[146:149], v110 offset:26624
	ds_read_b128 v[244:247], v110 offset:26688
	ds_read_b128 v[220:223], v110 offset:29184
	ds_read_b128 v[224:227], v110 offset:29248
	s_waitcnt lgkmcnt(3)
	v_mfma_f32_16x16x32_bf16 v[134:137], v[146:149], v[198:201], v[134:137]
	v_mfma_f32_16x16x32_bf16 v[118:121], v[146:149], v[210:213], v[118:121]
	ds_read_b128 v[146:149], v110 offset:31744
	s_waitcnt lgkmcnt(3)
	v_mfma_f32_16x16x32_bf16 v[134:137], v[244:247], v[192:195], v[134:137]
	v_mfma_f32_16x16x32_bf16 v[118:121], v[244:247], v[142:145], v[118:121]
	ds_read_b128 v[244:247], v110 offset:31808
	s_waitcnt lgkmcnt(3)
	v_mfma_f32_16x16x32_bf16 v[106:109], v[220:223], v[198:201], v[106:109]
	v_mfma_f32_16x16x32_bf16 v[102:105], v[220:223], v[210:213], v[102:105]
	ds_read_b128 v[220:223], v110 offset:34304
	s_waitcnt lgkmcnt(3)
	v_mfma_f32_16x16x32_bf16 v[106:109], v[224:227], v[192:195], v[106:109]
	v_mfma_f32_16x16x32_bf16 v[102:105], v[224:227], v[142:145], v[102:105]
	ds_read_b128 v[224:227], v110 offset:34368
	s_waitcnt lgkmcnt(3)
	v_mfma_f32_16x16x32_bf16 v[98:101], v[146:149], v[198:201], v[98:101]
	v_mfma_f32_16x16x32_bf16 v[94:97], v[146:149], v[210:213], v[94:97]
	ds_read_b128 v[146:149], v110 offset:36864
	s_waitcnt lgkmcnt(3)
	v_mfma_f32_16x16x32_bf16 v[98:101], v[244:247], v[192:195], v[98:101]
	v_mfma_f32_16x16x32_bf16 v[94:97], v[244:247], v[142:145], v[94:97]
	ds_read_b128 v[244:247], v110 offset:36928
	s_waitcnt lgkmcnt(3)
	v_mfma_f32_16x16x32_bf16 v[90:93], v[220:223], v[198:201], v[90:93]
	v_mfma_f32_16x16x32_bf16 v[86:89], v[220:223], v[210:213], v[86:89]
	ds_read_b128 v[220:223], v110 offset:39424
	s_waitcnt lgkmcnt(3)
	v_mfma_f32_16x16x32_bf16 v[90:93], v[224:227], v[192:195], v[90:93]
	v_mfma_f32_16x16x32_bf16 v[86:89], v[224:227], v[142:145], v[86:89]
	ds_read_b128 v[224:227], v110 offset:39488
	s_waitcnt lgkmcnt(3)
	v_mfma_f32_16x16x32_bf16 v[82:85], v[146:149], v[198:201], v[82:85]
	v_mfma_f32_16x16x32_bf16 v[78:81], v[146:149], v[210:213], v[78:81]
	ds_read_b128 v[146:149], v110 offset:41984
	s_waitcnt lgkmcnt(3)
	v_mfma_f32_16x16x32_bf16 v[82:85], v[244:247], v[192:195], v[82:85]
	v_mfma_f32_16x16x32_bf16 v[78:81], v[244:247], v[142:145], v[78:81]
	ds_read_b128 v[244:247], v110 offset:42048
	s_waitcnt lgkmcnt(3)
	v_mfma_f32_16x16x32_bf16 v[70:73], v[220:223], v[198:201], v[70:73]
	v_mfma_f32_16x16x32_bf16 v[74:77], v[220:223], v[210:213], v[74:77]
	ds_read_b128 v[220:223], v110 offset:44544
	s_waitcnt lgkmcnt(3)
	v_mfma_f32_16x16x32_bf16 v[70:73], v[224:227], v[192:195], v[70:73]
	v_mfma_f32_16x16x32_bf16 v[74:77], v[224:227], v[142:145], v[74:77]
	ds_read_b128 v[224:227], v110 offset:44608
	s_waitcnt lgkmcnt(3)
	v_mfma_f32_16x16x32_bf16 v[66:69], v[146:149], v[198:201], v[66:69]
	v_mfma_f32_16x16x32_bf16 v[58:61], v[146:149], v[210:213], v[58:61]
	s_waitcnt lgkmcnt(2)
	v_mfma_f32_16x16x32_bf16 v[66:69], v[244:247], v[192:195], v[66:69]
	v_mfma_f32_16x16x32_bf16 v[58:61], v[244:247], v[142:145], v[58:61]
	s_waitcnt lgkmcnt(1)
	v_mfma_f32_16x16x32_bf16 v[54:57], v[220:223], v[198:201], v[54:57]
	v_mfma_f32_16x16x32_bf16 v[62:65], v[220:223], v[210:213], v[62:65]
	s_waitcnt lgkmcnt(0)
	v_mfma_f32_16x16x32_bf16 v[54:57], v[224:227], v[192:195], v[54:57]
	v_mfma_f32_16x16x32_bf16 v[62:65], v[224:227], v[142:145], v[62:65]
; #define MFMA16(a, b, c) __builtin_amdgcn_mfma_f32_16x16x32_bf16((a), (b), (c), 0, 0, 0)
; DI void u_attn2(Frame& F, int h, int qb, int sp, int ntile) {
;     ...
;             {
;                 bf16x8 kfr[2][4];
; #pragma unroll
;                 for (int kb = 0; kb < 4; ++kb) kfr[0][kb] = ldfrag(Ks, 200, kb * 16, 0, lane);
; #pragma unroll
;                 for (int ks = 0; ks < 6; ++ks) {
;                     if (ks < 5) {
; #pragma unroll
;                         for (int kb = 0; kb < 4; ++kb) kfr[(ks + 1) & 1][kb] = ldfrag(Ks, 200, kb * 16, (ks + 1) * 32, lane); }
; #pragma unroll
;                     for (int kb = 0; kb < 4; ++kb)
; #pragma unroll
;                         for (int qq = 0; qq < 2; ++qq) s[kb][qq] = MFMA16(kfr[ks & 1][kb], qf[qq][ks], s[kb][qq]);
;                 }
;             }
.Latt_B_qk:
	v_cmp_lt_i32_e32 vcc, s46, v179
	s_cbranch_vccz .LBB0_2236
	v_add_u32_e32 v18, s46, v181
	v_cmp_le_i32_e32 vcc, v18, v180
	s_cbranch_vccz .LBB0_2236
	ds_read_b128 v[138:141], v113
	ds_read_b128 v[142:145], v113 offset:6656
	ds_read_b128 v[146:149], v113 offset:13312
	ds_read_b128 v[150:153], v113 offset:19968
	ds_read_b128 v[154:157], v113 offset:64
	ds_read_b128 v[192:195], v113 offset:6720
	ds_read_b128 v[210:213], v113 offset:13376
	ds_read_b128 v[214:217], v113 offset:20032
	s_waitcnt lgkmcnt(7)
	v_mfma_f32_16x16x32_bf16 v[218:221], v[138:141], v[2:5], 0
	ds_read_b128 v[244:247], v113 offset:128
	ds_read_b128 v[248:251], v113 offset:6784
	ds_read_b128 v[198:201], v113 offset:13440
	ds_read_b128 v[230:233], v113 offset:20096
	v_mov_b32_e32 v234, 0x42800000
	v_mfma_f32_16x16x32_bf16 v[138:141], v[138:141], v[30:33], 0
	s_waitcnt lgkmcnt(10)
	v_mfma_f32_16x16x32_bf16 v[222:225], v[142:145], v[2:5], 0
	v_mfma_f32_16x16x32_bf16 v[142:145], v[142:145], v[30:33], 0
	s_waitcnt lgkmcnt(9)
	v_mfma_f32_16x16x32_bf16 v[226:229], v[146:149], v[2:5], 0
	s_waitcnt lgkmcnt(7)
	v_mfma_f32_16x16x32_bf16 v[218:221], v[154:157], v[6:9], v[218:221]
	v_mfma_f32_16x16x32_bf16 v[146:149], v[146:149], v[30:33], 0
	v_mfma_f32_16x16x32_bf16 v[240:243], v[150:153], v[2:5], 0
	v_mfma_f32_16x16x32_bf16 v[150:153], v[150:153], v[30:33], 0
	v_mfma_f32_16x16x32_bf16 v[138:141], v[154:157], v[34:37], v[138:141]
	s_waitcnt lgkmcnt(6)
	v_mfma_f32_16x16x32_bf16 v[154:157], v[192:195], v[6:9], v[222:225]
	v_mfma_f32_16x16x32_bf16 v[142:145], v[192:195], v[34:37], v[142:145]
	s_waitcnt lgkmcnt(5)
	v_mfma_f32_16x16x32_bf16 v[192:195], v[210:213], v[6:9], v[226:229]
	s_waitcnt lgkmcnt(3)
	v_mfma_f32_16x16x32_bf16 v[218:221], v[244:247], v[10:13], v[218:221]
	v_mfma_f32_16x16x32_bf16 v[146:149], v[210:213], v[34:37], v[146:149]
	v_mfma_f32_16x16x32_bf16 v[210:213], v[214:217], v[6:9], v[240:243]
	v_mfma_f32_16x16x32_bf16 v[150:153], v[214:217], v[34:37], v[150:153]
	ds_read_b128 v[214:217], v113 offset:192
	ds_read_b128 v[222:225], v113 offset:6848
	ds_read_b128 v[226:229], v113 offset:13504
	ds_read_b128 v[240:243], v113 offset:20160
	v_mfma_f32_16x16x32_bf16 v[138:141], v[244:247], v[38:41], v[138:141]
	s_waitcnt lgkmcnt(6)
	v_mfma_f32_16x16x32_bf16 v[154:157], v[248:251], v[10:13], v[154:157]
	v_mfma_f32_16x16x32_bf16 v[142:145], v[248:251], v[38:41], v[142:145]
	s_waitcnt lgkmcnt(5)
	v_mfma_f32_16x16x32_bf16 v[192:195], v[198:201], v[10:13], v[192:195]
	s_waitcnt lgkmcnt(3)
	v_mfma_f32_16x16x32_bf16 v[218:221], v[214:217], v[14:17], v[218:221]
	v_mfma_f32_16x16x32_bf16 v[146:149], v[198:201], v[38:41], v[146:149]
	v_mfma_f32_16x16x32_bf16 v[198:201], v[230:233], v[10:13], v[210:213]
	v_mfma_f32_16x16x32_bf16 v[150:153], v[230:233], v[38:41], v[150:153]
	s_nop 1
	ds_read_b128 v[210:213], v113 offset:256
	ds_read_b128 v[230:233], v113 offset:6912
	ds_read_b128 v[244:247], v113 offset:13568
	ds_read_b128 v[248:251], v113 offset:20224
	v_mfma_f32_16x16x32_bf16 v[138:141], v[214:217], v[42:45], v[138:141]
	s_waitcnt lgkmcnt(6)
	v_mfma_f32_16x16x32_bf16 v[154:157], v[222:225], v[14:17], v[154:157]
	v_mfma_f32_16x16x32_bf16 v[142:145], v[222:225], v[42:45], v[142:145]
	s_waitcnt lgkmcnt(5)
	v_mfma_f32_16x16x32_bf16 v[192:195], v[226:229], v[14:17], v[192:195]
	s_waitcnt lgkmcnt(3)
	v_mfma_f32_16x16x32_bf16 v[218:221], v[210:213], v[22:25], v[218:221]
	v_mfma_f32_16x16x32_bf16 v[198:201], v[240:243], v[14:17], v[198:201]
	v_mfma_f32_16x16x32_bf16 v[150:153], v[240:243], v[42:45], v[150:153]
	v_mfma_f32_16x16x32_bf16 v[138:141], v[210:213], v[46:49], v[138:141]
	s_waitcnt lgkmcnt(2)
	v_mfma_f32_16x16x32_bf16 v[154:157], v[230:233], v[22:25], v[154:157]
	v_mfma_f32_16x16x32_bf16 v[146:149], v[226:229], v[42:45], v[146:149]
	ds_read_b128 v[214:217], v113 offset:320
	ds_read_b128 v[222:225], v113 offset:6976
	ds_read_b128 v[226:229], v113 offset:13632
	ds_read_b128 v[240:243], v113 offset:20288
	v_mfma_f32_16x16x32_bf16 v[142:145], v[230:233], v[46:49], v[142:145]
	s_waitcnt lgkmcnt(5)
	v_mfma_f32_16x16x32_bf16 v[192:195], v[244:247], v[22:25], v[192:195]
	s_waitcnt lgkmcnt(3)
	v_mfma_f32_16x16x32_bf16 v[218:221], v[214:217], v[26:29], v[218:221]
	v_mfma_f32_16x16x32_bf16 v[198:201], v[248:251], v[22:25], v[198:201]
	v_mfma_f32_16x16x32_bf16 v[230:233], v[248:251], v[46:49], v[150:153]
	v_mfma_f32_16x16x32_bf16 v[150:153], v[214:217], v[50:53], v[138:141]
	s_waitcnt lgkmcnt(2)
	v_mfma_f32_16x16x32_bf16 v[214:217], v[222:225], v[26:29], v[154:157]
	v_mfma_f32_16x16x32_bf16 v[210:213], v[244:247], v[46:49], v[146:149]
	v_mfma_f32_16x16x32_bf16 v[146:149], v[222:225], v[50:53], v[142:145]
	s_waitcnt lgkmcnt(1)
	v_mfma_f32_16x16x32_bf16 v[222:225], v[226:229], v[26:29], v[192:195]
	s_waitcnt lgkmcnt(0)
	v_mfma_f32_16x16x32_bf16 v[154:157], v[240:243], v[26:29], v[198:201]
	v_mfma_f32_16x16x32_bf16 v[138:141], v[240:243], v[50:53], v[230:233]
	s_nop 1
	v_mfma_f32_16x16x32_bf16 v[142:145], v[226:229], v[50:53], v[210:213]
	s_branch .LBB0_2236
